# row-scale staging of the P1/P7 epilogues done by the leading wave half before its end-of-unit alignment barrier (overlaps the trailing half's last MFMA block); epilogue staging barrier removed
# speedup vs baseline: 1.0012x; 1.0012x over previous
.LBB0_316:
	s_add_u32 s30, s28, 0xfffc0080
	s_addc_u32 s31, s29, -1
	s_add_i32 s63, 0, 0x10000
	s_cmp_eq_u32 s62, 12
	s_cselect_b32 s35, s25, s31
	s_cselect_b32 s34, s58, s30
	v_add_u32_e32 v142, s63, v145
	s_cselect_b32 s31, s23, s61
	s_cselect_b32 s30, s59, s60
	s_add_i32 s66, 0, 0x14000
	ds_read_b128 v[148:151], v142
	ds_read_b128 v[152:155], v142 offset:1024
	ds_read_b128 v[156:159], v142 offset:2048
	ds_read_b128 v[160:163], v142 offset:3072
	v_add_u32_e32 v142, s66, v145
	ds_read_b128 v[164:167], v142
	ds_read_b128 v[168:171], v142 offset:1024
	ds_read_b128 v[172:175], v142 offset:2048
	ds_read_b128 v[176:179], v142 offset:3072
	v_lshl_add_u64 v[142:143], s[28:29], 0, v[138:139]
	s_add_i32 m0, s45, 0xc000
	ds_read_b128 v[180:183], v146
	ds_read_b128 v[184:187], v146 offset:1024
	ds_read_b128 v[188:191], v146 offset:2048
	ds_read_b128 v[192:195], v146 offset:3072
	ds_read_b128 v[206:209], v146 offset:4096
	ds_read_b128 v[210:213], v146 offset:5120
	ds_read_b128 v[214:217], v146 offset:6144
	ds_read_b128 v[218:221], v146 offset:7168
	global_load_lds_dwordx4 v[142:143], off
	v_lshl_add_u64 v[142:143], s[28:29], 0, v[140:141]
	s_add_i32 m0, s45, 0xe000
	s_nop 0
	global_load_lds_dwordx4 v[142:143], off
	s_waitcnt vmcnt(8)
	s_waitcnt lgkmcnt(0)
	s_barrier
	s_waitcnt lgkmcnt(0)
	v_mfma_f32_16x16x32_bf16 v[128:131], v[148:151], v[180:183], v[128:131]
	v_mfma_f32_16x16x32_bf16 v[120:123], v[156:159], v[180:183], v[120:123]
	v_mfma_f32_16x16x32_bf16 v[112:115], v[148:151], v[188:191], v[112:115]
	v_mfma_f32_16x16x32_bf16 v[104:107], v[156:159], v[188:191], v[104:107]
	v_mfma_f32_16x16x32_bf16 v[96:99], v[148:151], v[206:209], v[96:99]
	v_mfma_f32_16x16x32_bf16 v[88:91], v[156:159], v[206:209], v[88:91]
	v_mfma_f32_16x16x32_bf16 v[80:83], v[148:151], v[214:217], v[80:83]
	v_mfma_f32_16x16x32_bf16 v[72:75], v[156:159], v[214:217], v[72:75]
	v_mfma_f32_16x16x32_bf16 v[128:131], v[152:155], v[184:187], v[128:131]
	v_mfma_f32_16x16x32_bf16 v[120:123], v[160:163], v[184:187], v[120:123]
	v_mfma_f32_16x16x32_bf16 v[112:115], v[152:155], v[192:195], v[112:115]
	v_mfma_f32_16x16x32_bf16 v[104:107], v[160:163], v[192:195], v[104:107]
	v_mfma_f32_16x16x32_bf16 v[96:99], v[152:155], v[210:213], v[96:99]
	v_mfma_f32_16x16x32_bf16 v[88:91], v[160:163], v[210:213], v[88:91]
	v_mfma_f32_16x16x32_bf16 v[80:83], v[152:155], v[218:221], v[80:83]
	v_mfma_f32_16x16x32_bf16 v[72:75], v[160:163], v[218:221], v[72:75]
	v_mfma_f32_16x16x32_bf16 v[124:127], v[164:167], v[180:183], v[124:127]
	v_mfma_f32_16x16x32_bf16 v[116:119], v[172:175], v[180:183], v[116:119]
	v_mfma_f32_16x16x32_bf16 v[108:111], v[164:167], v[188:191], v[108:111]
	v_mfma_f32_16x16x32_bf16 v[100:103], v[172:175], v[188:191], v[100:103]
	v_mfma_f32_16x16x32_bf16 v[92:95], v[164:167], v[206:209], v[92:95]
	v_mfma_f32_16x16x32_bf16 v[84:87], v[172:175], v[206:209], v[84:87]
	v_mfma_f32_16x16x32_bf16 v[76:79], v[164:167], v[214:217], v[76:79]
	v_mfma_f32_16x16x32_bf16 v[68:71], v[172:175], v[214:217], v[68:71]
	v_mfma_f32_16x16x32_bf16 v[124:127], v[168:171], v[184:187], v[124:127]
	v_mfma_f32_16x16x32_bf16 v[116:119], v[176:179], v[184:187], v[116:119]
	v_mfma_f32_16x16x32_bf16 v[108:111], v[168:171], v[192:195], v[108:111]
	v_mfma_f32_16x16x32_bf16 v[100:103], v[176:179], v[192:195], v[100:103]
	v_mfma_f32_16x16x32_bf16 v[92:95], v[168:171], v[210:213], v[92:95]
	v_mfma_f32_16x16x32_bf16 v[84:87], v[176:179], v[210:213], v[84:87]
	v_mfma_f32_16x16x32_bf16 v[76:79], v[168:171], v[218:221], v[76:79]
	v_mfma_f32_16x16x32_bf16 v[68:71], v[176:179], v[218:221], v[68:71]
	s_barrier
	s_add_i32 s63, s63, s36
	v_lshl_add_u64 v[142:143], s[30:31], 0, v[2:3]
	s_mov_b32 m0, s63
	ds_read_b128 v[180:183], v146 offset:16384
	ds_read_b128 v[184:187], v146 offset:17408
	ds_read_b128 v[188:191], v146 offset:18432
	ds_read_b128 v[192:195], v146 offset:19456
	ds_read_b128 v[206:209], v146 offset:20480
	ds_read_b128 v[210:213], v146 offset:21504
	ds_read_b128 v[214:217], v146 offset:22528
	ds_read_b128 v[218:221], v146 offset:23552
	global_load_lds_dwordx4 v[142:143], off
	s_add_i32 m0, s63, 0x2000
	s_add_u32 s64, s30, 0x40000
	v_lshl_add_u64 v[236:237], s[30:31], 0, v[132:133]
	s_addc_u32 s65, s31, 0
	s_add_i32 s63, s66, s36
	global_load_lds_dwordx4 v[236:237], off
	v_lshl_add_u64 v[238:239], s[64:65], 0, v[2:3]
	s_mov_b32 m0, s63
	v_lshl_add_u64 v[240:241], s[34:35], 0, v[134:135]
	global_load_lds_dwordx4 v[238:239], off
	v_lshl_add_u64 v[238:239], s[64:65], 0, v[132:133]
	s_add_i32 m0, s63, 0x2000
	s_nop 0
	global_load_lds_dwordx4 v[238:239], off
	v_lshl_add_u64 v[238:239], s[34:35], 0, v[136:137]
	s_mov_b32 m0, s45
	s_nop 0
	global_load_lds_dwordx4 v[238:239], off
	s_mov_b32 m0, s46
	s_nop 0
	global_load_lds_dwordx4 v[240:241], off
	s_waitcnt vmcnt(8)
	s_waitcnt lgkmcnt(0)
	s_barrier
	s_waitcnt lgkmcnt(0)
	v_mfma_f32_16x16x32_bf16 v[64:67], v[148:151], v[180:183], v[64:67]
	v_mfma_f32_16x16x32_bf16 v[56:59], v[156:159], v[180:183], v[56:59]
	v_mfma_f32_16x16x32_bf16 v[48:51], v[148:151], v[188:191], v[48:51]
	v_mfma_f32_16x16x32_bf16 v[40:43], v[156:159], v[188:191], v[40:43]
	v_mfma_f32_16x16x32_bf16 v[32:35], v[148:151], v[206:209], v[32:35]
	v_mfma_f32_16x16x32_bf16 v[24:27], v[156:159], v[206:209], v[24:27]
	v_mfma_f32_16x16x32_bf16 v[16:19], v[148:151], v[214:217], v[16:19]
	v_mfma_f32_16x16x32_bf16 v[8:11], v[156:159], v[214:217], v[8:11]
	v_mfma_f32_16x16x32_bf16 v[64:67], v[152:155], v[184:187], v[64:67]
	v_mfma_f32_16x16x32_bf16 v[56:59], v[160:163], v[184:187], v[56:59]
	v_mfma_f32_16x16x32_bf16 v[48:51], v[152:155], v[192:195], v[48:51]
	v_mfma_f32_16x16x32_bf16 v[40:43], v[160:163], v[192:195], v[40:43]
	v_mfma_f32_16x16x32_bf16 v[32:35], v[152:155], v[210:213], v[32:35]
	v_mfma_f32_16x16x32_bf16 v[24:27], v[160:163], v[210:213], v[24:27]
	v_mfma_f32_16x16x32_bf16 v[16:19], v[152:155], v[218:221], v[16:19]
	v_mfma_f32_16x16x32_bf16 v[8:11], v[160:163], v[218:221], v[8:11]
	v_mfma_f32_16x16x32_bf16 v[60:63], v[164:167], v[180:183], v[60:63]
	v_mfma_f32_16x16x32_bf16 v[52:55], v[172:175], v[180:183], v[52:55]
	v_mfma_f32_16x16x32_bf16 v[44:47], v[164:167], v[188:191], v[44:47]
	v_mfma_f32_16x16x32_bf16 v[36:39], v[172:175], v[188:191], v[36:39]
	v_mfma_f32_16x16x32_bf16 v[28:31], v[164:167], v[206:209], v[28:31]
	v_mfma_f32_16x16x32_bf16 v[20:23], v[172:175], v[206:209], v[20:23]
	v_mfma_f32_16x16x32_bf16 v[12:15], v[164:167], v[214:217], v[12:15]
	v_mfma_f32_16x16x32_bf16 v[4:7], v[172:175], v[214:217], v[4:7]
	v_mfma_f32_16x16x32_bf16 v[60:63], v[168:171], v[184:187], v[60:63]
	v_mfma_f32_16x16x32_bf16 v[52:55], v[176:179], v[184:187], v[52:55]
	v_mfma_f32_16x16x32_bf16 v[44:47], v[168:171], v[192:195], v[44:47]
	v_mfma_f32_16x16x32_bf16 v[36:39], v[176:179], v[192:195], v[36:39]
	v_mfma_f32_16x16x32_bf16 v[28:31], v[168:171], v[210:213], v[28:31]
	v_mfma_f32_16x16x32_bf16 v[20:23], v[176:179], v[210:213], v[20:23]
	v_mfma_f32_16x16x32_bf16 v[12:15], v[168:171], v[218:221], v[12:15]
	v_mfma_f32_16x16x32_bf16 v[4:7], v[176:179], v[218:221], v[4:7]
	s_barrier
	s_add_i32 s63, 0, 0x18000
	v_add_u32_e32 v147, s63, v145
	s_add_i32 s64, 0, 0x1c000
	ds_read_b128 v[148:151], v147
	ds_read_b128 v[152:155], v147 offset:1024
	ds_read_b128 v[156:159], v147 offset:2048
	ds_read_b128 v[160:163], v147 offset:3072
	v_add_u32_e32 v147, s64, v145
	ds_read_b128 v[164:167], v147
	ds_read_b128 v[168:171], v147 offset:1024
	ds_read_b128 v[172:175], v147 offset:2048
	ds_read_b128 v[176:179], v147 offset:3072
	s_add_u32 s34, s34, 0x40000
	s_addc_u32 s35, s35, 0
	s_mov_b32 m0, s47
	v_lshl_add_u64 v[242:243], s[34:35], 0, v[136:137]
	ds_read_b128 v[180:183], v146 offset:32768
	ds_read_b128 v[184:187], v146 offset:33792
	ds_read_b128 v[188:191], v146 offset:34816
	ds_read_b128 v[192:195], v146 offset:35840
	ds_read_b128 v[206:209], v146 offset:36864
	ds_read_b128 v[210:213], v146 offset:37888
	ds_read_b128 v[214:217], v146 offset:38912
	ds_read_b128 v[218:221], v146 offset:39936
	global_load_lds_dwordx4 v[242:243], off
	v_lshl_add_u64 v[242:243], s[34:35], 0, v[134:135]
	s_mov_b32 m0, s48
	s_nop 0
	global_load_lds_dwordx4 v[242:243], off
	s_waitcnt vmcnt(8)
	s_waitcnt lgkmcnt(0)
	s_barrier
	s_waitcnt lgkmcnt(0)
	v_mfma_f32_16x16x32_bf16 v[128:131], v[148:151], v[180:183], v[128:131]
	v_mfma_f32_16x16x32_bf16 v[120:123], v[156:159], v[180:183], v[120:123]
	v_mfma_f32_16x16x32_bf16 v[112:115], v[148:151], v[188:191], v[112:115]
	v_mfma_f32_16x16x32_bf16 v[104:107], v[156:159], v[188:191], v[104:107]
	v_mfma_f32_16x16x32_bf16 v[96:99], v[148:151], v[206:209], v[96:99]
	v_mfma_f32_16x16x32_bf16 v[88:91], v[156:159], v[206:209], v[88:91]
	v_mfma_f32_16x16x32_bf16 v[80:83], v[148:151], v[214:217], v[80:83]
	v_mfma_f32_16x16x32_bf16 v[72:75], v[156:159], v[214:217], v[72:75]
	v_mfma_f32_16x16x32_bf16 v[128:131], v[152:155], v[184:187], v[128:131]
	v_mfma_f32_16x16x32_bf16 v[120:123], v[160:163], v[184:187], v[120:123]
	v_mfma_f32_16x16x32_bf16 v[112:115], v[152:155], v[192:195], v[112:115]
	v_mfma_f32_16x16x32_bf16 v[104:107], v[160:163], v[192:195], v[104:107]
	v_mfma_f32_16x16x32_bf16 v[96:99], v[152:155], v[210:213], v[96:99]
	v_mfma_f32_16x16x32_bf16 v[88:91], v[160:163], v[210:213], v[88:91]
	v_mfma_f32_16x16x32_bf16 v[80:83], v[152:155], v[218:221], v[80:83]
	v_mfma_f32_16x16x32_bf16 v[72:75], v[160:163], v[218:221], v[72:75]
	v_mfma_f32_16x16x32_bf16 v[124:127], v[164:167], v[180:183], v[124:127]
	v_mfma_f32_16x16x32_bf16 v[116:119], v[172:175], v[180:183], v[116:119]
	v_mfma_f32_16x16x32_bf16 v[108:111], v[164:167], v[188:191], v[108:111]
	v_mfma_f32_16x16x32_bf16 v[100:103], v[172:175], v[188:191], v[100:103]
	v_mfma_f32_16x16x32_bf16 v[92:95], v[164:167], v[206:209], v[92:95]
	v_mfma_f32_16x16x32_bf16 v[84:87], v[172:175], v[206:209], v[84:87]
	v_mfma_f32_16x16x32_bf16 v[76:79], v[164:167], v[214:217], v[76:79]
	v_mfma_f32_16x16x32_bf16 v[68:71], v[172:175], v[214:217], v[68:71]
	v_mfma_f32_16x16x32_bf16 v[124:127], v[168:171], v[184:187], v[124:127]
	v_mfma_f32_16x16x32_bf16 v[116:119], v[176:179], v[184:187], v[116:119]
	v_mfma_f32_16x16x32_bf16 v[108:111], v[168:171], v[192:195], v[108:111]
	v_mfma_f32_16x16x32_bf16 v[100:103], v[176:179], v[192:195], v[100:103]
	v_mfma_f32_16x16x32_bf16 v[92:95], v[168:171], v[210:213], v[92:95]
	v_mfma_f32_16x16x32_bf16 v[84:87], v[176:179], v[210:213], v[84:87]
	v_mfma_f32_16x16x32_bf16 v[76:79], v[168:171], v[218:221], v[76:79]
	v_mfma_f32_16x16x32_bf16 v[68:71], v[176:179], v[218:221], v[68:71]
	s_barrier
	s_add_i32 s34, s63, s36
	v_lshl_add_u64 v[142:143], v[142:143], 0, s[96:97]
	s_mov_b32 m0, s34
	ds_read_b128 v[180:183], v146 offset:49152
	ds_read_b128 v[184:187], v146 offset:50176
	ds_read_b128 v[188:191], v146 offset:51200
	ds_read_b128 v[192:195], v146 offset:52224
	ds_read_b128 v[206:209], v146 offset:53248
	ds_read_b128 v[210:213], v146 offset:54272
	ds_read_b128 v[214:217], v146 offset:55296
	ds_read_b128 v[218:221], v146 offset:56320
	global_load_lds_dwordx4 v[142:143], off
	s_add_i32 m0, s34, 0x2000
	s_add_u32 s30, s30, 0x40080
	v_lshl_add_u64 v[142:143], v[236:237], 0, s[96:97]
	s_addc_u32 s31, s31, 0
	s_add_i32 s34, s64, s36
	global_load_lds_dwordx4 v[142:143], off
	v_lshl_add_u64 v[142:143], s[30:31], 0, v[2:3]
	s_mov_b32 m0, s34
	s_nop 0
	global_load_lds_dwordx4 v[142:143], off
	v_lshl_add_u64 v[142:143], s[30:31], 0, v[132:133]
	s_add_i32 m0, s34, 0x2000
	s_nop 0
	global_load_lds_dwordx4 v[142:143], off
	v_lshl_add_u64 v[142:143], v[238:239], 0, s[96:97]
	s_mov_b32 m0, s51
	s_nop 0
	global_load_lds_dwordx4 v[142:143], off
	v_lshl_add_u64 v[142:143], v[240:241], 0, s[96:97]
	s_mov_b32 m0, s52
	s_nop 0
	global_load_lds_dwordx4 v[142:143], off
	s_waitcnt vmcnt(8)
	s_waitcnt lgkmcnt(0)
	s_barrier
	s_waitcnt lgkmcnt(0)
	v_mfma_f32_16x16x32_bf16 v[64:67], v[148:151], v[180:183], v[64:67]
	v_mfma_f32_16x16x32_bf16 v[56:59], v[156:159], v[180:183], v[56:59]
	v_mfma_f32_16x16x32_bf16 v[48:51], v[148:151], v[188:191], v[48:51]
	v_mfma_f32_16x16x32_bf16 v[40:43], v[156:159], v[188:191], v[40:43]
	v_mfma_f32_16x16x32_bf16 v[32:35], v[148:151], v[206:209], v[32:35]
	v_mfma_f32_16x16x32_bf16 v[24:27], v[156:159], v[206:209], v[24:27]
	v_mfma_f32_16x16x32_bf16 v[16:19], v[148:151], v[214:217], v[16:19]
	v_mfma_f32_16x16x32_bf16 v[8:11], v[156:159], v[214:217], v[8:11]
	v_mfma_f32_16x16x32_bf16 v[64:67], v[152:155], v[184:187], v[64:67]
	v_mfma_f32_16x16x32_bf16 v[56:59], v[160:163], v[184:187], v[56:59]
	v_mfma_f32_16x16x32_bf16 v[48:51], v[152:155], v[192:195], v[48:51]
	v_mfma_f32_16x16x32_bf16 v[40:43], v[160:163], v[192:195], v[40:43]
	v_mfma_f32_16x16x32_bf16 v[32:35], v[152:155], v[210:213], v[32:35]
	v_mfma_f32_16x16x32_bf16 v[24:27], v[160:163], v[210:213], v[24:27]
	v_mfma_f32_16x16x32_bf16 v[16:19], v[152:155], v[218:221], v[16:19]
	v_mfma_f32_16x16x32_bf16 v[8:11], v[160:163], v[218:221], v[8:11]
	v_mfma_f32_16x16x32_bf16 v[60:63], v[164:167], v[180:183], v[60:63]
	v_mfma_f32_16x16x32_bf16 v[52:55], v[172:175], v[180:183], v[52:55]
	v_mfma_f32_16x16x32_bf16 v[44:47], v[164:167], v[188:191], v[44:47]
	v_mfma_f32_16x16x32_bf16 v[36:39], v[172:175], v[188:191], v[36:39]
	v_mfma_f32_16x16x32_bf16 v[28:31], v[164:167], v[206:209], v[28:31]
	v_mfma_f32_16x16x32_bf16 v[20:23], v[172:175], v[206:209], v[20:23]
	v_mfma_f32_16x16x32_bf16 v[12:15], v[164:167], v[214:217], v[12:15]
	v_mfma_f32_16x16x32_bf16 v[4:7], v[172:175], v[214:217], v[4:7]
	v_mfma_f32_16x16x32_bf16 v[60:63], v[168:171], v[184:187], v[60:63]
	v_mfma_f32_16x16x32_bf16 v[52:55], v[176:179], v[184:187], v[52:55]
	v_mfma_f32_16x16x32_bf16 v[44:47], v[168:171], v[192:195], v[44:47]
	v_mfma_f32_16x16x32_bf16 v[36:39], v[176:179], v[192:195], v[36:39]
	v_mfma_f32_16x16x32_bf16 v[28:31], v[168:171], v[210:213], v[28:31]
	v_mfma_f32_16x16x32_bf16 v[20:23], v[176:179], v[210:213], v[20:23]
	v_mfma_f32_16x16x32_bf16 v[12:15], v[168:171], v[218:221], v[12:15]
	v_mfma_f32_16x16x32_bf16 v[4:7], v[176:179], v[218:221], v[4:7]
	s_barrier
	s_add_i32 s62, s62, 2
	s_add_u32 s28, s28, 0x100
	s_addc_u32 s29, s29, 0
	s_add_u32 s60, s60, 0x100
	s_addc_u32 s61, s61, 0
	s_cmp_gt_u32 s62, 13
	s_cbranch_scc0 .LBB0_316
	s_and_b64 vcc, exec, s[16:17]
	s_cbranch_vccz .LBB0_319
	v_lshl_add_u32 v147, v144, 4, v1
	v_add_u32_e32 v147, s53, v147
	v_lshlrev_b32_e32 v160, 6, v147
	v_add_u32_e32 v160, 0x20400, v160
	ds_read_b128 v[148:151], v160
	ds_read_b128 v[152:155], v160 offset:32
	ds_read_b128 v[156:159], v160 offset:16
	ds_read_b128 v[160:163], v160 offset:48
	s_mov_b32 s25, 0x800000
	v_lshl_add_u32 v147, v147, 2, v225
	s_waitcnt lgkmcnt(0)
	v_mov_b32_e32 v164, v148
	v_mov_b32_e32 v165, v152
	v_mov_b32_e32 v152, v149
	v_mov_b32_e32 v148, v150
	v_mov_b32_e32 v149, v154
	v_mov_b32_e32 v154, v151
	v_mov_b32_e32 v150, v156
	v_mov_b32_e32 v151, v160
	v_mov_b32_e32 v160, v157
	v_mov_b32_e32 v156, v158
	v_mov_b32_e32 v157, v162
	v_mov_b32_e32 v162, v159
	v_pk_add_f32 v[152:153], v[164:165], v[152:153]
	v_pk_add_f32 v[148:149], v[148:149], v[154:155]
	v_pk_add_f32 v[150:151], v[150:151], v[160:161]
	v_pk_add_f32 v[154:155], v[156:157], v[162:163]
	v_pk_add_f32 v[148:149], v[152:153], v[148:149]
	v_pk_add_f32 v[150:151], v[150:151], v[154:155]
	s_nop 0
	v_pk_add_f32 v[148:149], v[148:149], v[150:151]
	s_nop 0
	v_add_f32_e32 v148, v148, v149
	v_fmamk_f32 v148, v148, 0x3a800000, v223
	ds_write_b32 v147, v148 offset:17408
	v_mul_f32_e32 v149, 0x4b800000, v148
	v_cmp_gt_f32_e32 vcc, s25, v148
	s_nop 1
	v_cndmask_b32_e32 v148, v148, v149, vcc
	v_rsq_f32_e32 v148, v148
	s_nop 0
	v_mul_f32_e32 v149, 0x45800000, v148
	v_cndmask_b32_e32 v148, v148, v149, vcc
	ds_write_b32 v147, v148
	s_waitcnt lgkmcnt(0)
	s_barrier

.LBB0_321:
	s_nop 0
	s_lshl_b32 s25, s56, 7
	v_and_b32_e32 v148, 3, v142
	s_or_b32 s25, s25, s50
	v_lshl_or_b32 v150, v148, 3, s25
	v_ashrrev_i32_e32 v147, 2, v143
	v_and_b32_e32 v143, -4, v143
	s_nop 0
	s_nop 0
	v_lshl_add_u32 v149, v142, 2, s54
	v_ashrrev_i32_e32 v151, 31, v150
	v_lshl_add_u32 v148, v148, 6, v143
	v_lshl_add_u64 v[142:143], v[150:151], 1, s[20:21]
	ds_read_b32 v160, v149
	ds_read_b32 v161, v149 offset:64
	ds_read_b32 v162, v149 offset:128
	ds_read_b32 v163, v149 offset:192
	ds_read_b32 v164, v149 offset:512
	ds_read_b32 v165, v149 offset:576
	ds_read_b32 v166, v149 offset:640
	ds_read_b32 v167, v149 offset:704
	ds_read_b32 v206, v149 offset:17408
	ds_read_b32 v208, v149 offset:17472
	ds_read_b32 v210, v149 offset:17536
	ds_read_b32 v212, v149 offset:17600
	ds_read_b32 v214, v149 offset:17920
	ds_read_b32 v216, v149 offset:17984
	ds_read_b32 v218, v149 offset:18048
	ds_read_b32 v220, v149 offset:18112
	s_add_i32 s23, s23, s49
	v_add_u32_e32 v147, s23, v147
	s_movk_i32 s23, 0x1600
	s_nop 0
	v_mad_i64_i32 v[192:193], s[28:29], v147, s23, v[142:143]
	s_mov_b32 s28, 0x16000
	s_mov_b32 s29, 0
	s_waitcnt lgkmcnt(0)
	v_mul_f32_e32 v170, 0xbfb8aa3b, v160
	v_mul_f32_e32 v172, 0xbfb8aa3b, v161
	v_mul_f32_e32 v174, 0xbfb8aa3b, v162
	v_mul_f32_e32 v176, 0xbfb8aa3b, v163
	v_mul_f32_e32 v178, 0xbfb8aa3b, v164
	v_mul_f32_e32 v180, 0xbfb8aa3b, v165
	v_mul_f32_e32 v182, 0xbfb8aa3b, v166
	v_mul_f32_e32 v184, 0xbfb8aa3b, v167
	v_pk_mul_f32 v[124:125], v[128:129], v[124:125]
	v_pk_mul_f32 v[126:127], v[130:131], v[126:127]
	v_pk_mul_f32 v[116:117], v[120:121], v[116:117]
	v_pk_mul_f32 v[118:119], v[122:123], v[118:119]
	v_pk_mul_f32 v[128:129], v[128:129], v[170:171] op_sel_hi:[1,0]
	v_pk_mul_f32 v[130:131], v[130:131], v[170:171] op_sel_hi:[1,0]
	v_pk_mul_f32 v[120:121], v[120:121], v[170:171] op_sel_hi:[1,0]
	v_pk_mul_f32 v[122:123], v[122:123], v[170:171] op_sel_hi:[1,0]
	v_exp_f32_e32 v128, v128
	v_exp_f32_e32 v129, v129
	v_exp_f32_e32 v130, v130
	v_exp_f32_e32 v131, v131
	v_exp_f32_e32 v120, v120
	v_exp_f32_e32 v121, v121
	v_exp_f32_e32 v122, v122
	v_exp_f32_e32 v123, v123
	v_pk_fma_f32 v[128:129], v[128:129], v[206:207], v[206:207] op_sel_hi:[1,0,0]
	v_pk_fma_f32 v[130:131], v[130:131], v[206:207], v[206:207] op_sel_hi:[1,0,0]
	v_pk_fma_f32 v[120:121], v[120:121], v[206:207], v[206:207] op_sel_hi:[1,0,0]
	v_pk_fma_f32 v[122:123], v[122:123], v[206:207], v[206:207] op_sel_hi:[1,0,0]
	v_rcp_f32_e32 v128, v128
	v_rcp_f32_e32 v129, v129
	v_rcp_f32_e32 v130, v130
	v_rcp_f32_e32 v131, v131
	v_rcp_f32_e32 v120, v120
	v_rcp_f32_e32 v121, v121
	v_rcp_f32_e32 v122, v122
	v_rcp_f32_e32 v123, v123
	v_pk_mul_f32 v[124:125], v[124:125], v[128:129]
	v_pk_mul_f32 v[126:127], v[126:127], v[130:131]
	v_pk_mul_f32 v[116:117], v[116:117], v[120:121]
	v_pk_mul_f32 v[118:119], v[118:119], v[122:123]
	v_cvt_pk_bf16_f32 v120, v124, v125
	v_cvt_pk_bf16_f32 v121, v126, v127
	v_cvt_pk_bf16_f32 v122, v116, v117
	v_cvt_pk_bf16_f32 v123, v118, v119
	ds_bpermute_b32 v128, v148, v120
	ds_bpermute_b32 v129, v148, v121
	ds_bpermute_b32 v130, v148, v122
	ds_bpermute_b32 v131, v148, v123
	v_pk_mul_f32 v[108:109], v[112:113], v[108:109]
	v_pk_mul_f32 v[110:111], v[114:115], v[110:111]
	v_pk_mul_f32 v[100:101], v[104:105], v[100:101]
	v_pk_mul_f32 v[102:103], v[106:107], v[102:103]
	v_pk_mul_f32 v[112:113], v[112:113], v[172:173] op_sel_hi:[1,0]
	v_pk_mul_f32 v[114:115], v[114:115], v[172:173] op_sel_hi:[1,0]
	v_pk_mul_f32 v[104:105], v[104:105], v[172:173] op_sel_hi:[1,0]
	v_pk_mul_f32 v[106:107], v[106:107], v[172:173] op_sel_hi:[1,0]
	v_exp_f32_e32 v112, v112
	v_exp_f32_e32 v113, v113
	v_exp_f32_e32 v114, v114
	v_exp_f32_e32 v115, v115
	v_exp_f32_e32 v104, v104
	v_exp_f32_e32 v105, v105
	v_exp_f32_e32 v106, v106
	v_exp_f32_e32 v107, v107
	v_pk_fma_f32 v[112:113], v[112:113], v[208:209], v[208:209] op_sel_hi:[1,0,0]
	v_pk_fma_f32 v[114:115], v[114:115], v[208:209], v[208:209] op_sel_hi:[1,0,0]
	v_pk_fma_f32 v[104:105], v[104:105], v[208:209], v[208:209] op_sel_hi:[1,0,0]
	v_pk_fma_f32 v[106:107], v[106:107], v[208:209], v[208:209] op_sel_hi:[1,0,0]
	v_rcp_f32_e32 v112, v112
	v_rcp_f32_e32 v113, v113
	v_rcp_f32_e32 v114, v114
	v_rcp_f32_e32 v115, v115
	v_rcp_f32_e32 v104, v104
	v_rcp_f32_e32 v105, v105
	v_rcp_f32_e32 v106, v106
	v_rcp_f32_e32 v107, v107
	v_pk_mul_f32 v[108:109], v[108:109], v[112:113]
	v_pk_mul_f32 v[110:111], v[110:111], v[114:115]
	v_pk_mul_f32 v[100:101], v[100:101], v[104:105]
	v_pk_mul_f32 v[102:103], v[102:103], v[106:107]
	v_cvt_pk_bf16_f32 v104, v108, v109
	v_cvt_pk_bf16_f32 v105, v110, v111
	v_cvt_pk_bf16_f32 v106, v100, v101
	v_cvt_pk_bf16_f32 v107, v102, v103
	s_waitcnt lgkmcnt(0)
	global_store_dwordx4 v[192:193], v[128:131], off
	v_lshl_add_u64 v[192:193], v[192:193], 0, s[28:29]
	ds_bpermute_b32 v112, v148, v104
	ds_bpermute_b32 v113, v148, v105
	ds_bpermute_b32 v114, v148, v106
	ds_bpermute_b32 v115, v148, v107
	v_pk_mul_f32 v[92:93], v[96:97], v[92:93]
	v_pk_mul_f32 v[94:95], v[98:99], v[94:95]
	v_pk_mul_f32 v[84:85], v[88:89], v[84:85]
	v_pk_mul_f32 v[86:87], v[90:91], v[86:87]
	v_pk_mul_f32 v[96:97], v[96:97], v[174:175] op_sel_hi:[1,0]
	v_pk_mul_f32 v[98:99], v[98:99], v[174:175] op_sel_hi:[1,0]
	v_pk_mul_f32 v[88:89], v[88:89], v[174:175] op_sel_hi:[1,0]
	v_pk_mul_f32 v[90:91], v[90:91], v[174:175] op_sel_hi:[1,0]
	v_exp_f32_e32 v96, v96
	v_exp_f32_e32 v97, v97
	v_exp_f32_e32 v98, v98
	v_exp_f32_e32 v99, v99
	v_exp_f32_e32 v88, v88
	v_exp_f32_e32 v89, v89
	v_exp_f32_e32 v90, v90
	v_exp_f32_e32 v91, v91
	v_pk_fma_f32 v[96:97], v[96:97], v[210:211], v[210:211] op_sel_hi:[1,0,0]
	v_pk_fma_f32 v[98:99], v[98:99], v[210:211], v[210:211] op_sel_hi:[1,0,0]
	v_pk_fma_f32 v[88:89], v[88:89], v[210:211], v[210:211] op_sel_hi:[1,0,0]
	v_pk_fma_f32 v[90:91], v[90:91], v[210:211], v[210:211] op_sel_hi:[1,0,0]
	v_rcp_f32_e32 v96, v96
	v_rcp_f32_e32 v97, v97
	v_rcp_f32_e32 v98, v98
	v_rcp_f32_e32 v99, v99
	v_rcp_f32_e32 v88, v88
	v_rcp_f32_e32 v89, v89
	v_rcp_f32_e32 v90, v90
	v_rcp_f32_e32 v91, v91
	v_pk_mul_f32 v[92:93], v[92:93], v[96:97]
	v_pk_mul_f32 v[94:95], v[94:95], v[98:99]
	v_pk_mul_f32 v[84:85], v[84:85], v[88:89]
	v_pk_mul_f32 v[86:87], v[86:87], v[90:91]
	v_cvt_pk_bf16_f32 v88, v92, v93
	v_cvt_pk_bf16_f32 v89, v94, v95
	v_cvt_pk_bf16_f32 v90, v84, v85
	v_cvt_pk_bf16_f32 v91, v86, v87
	s_waitcnt lgkmcnt(0)
	global_store_dwordx4 v[192:193], v[112:115], off
	v_lshl_add_u64 v[192:193], v[192:193], 0, s[28:29]
	ds_bpermute_b32 v96, v148, v88
	ds_bpermute_b32 v97, v148, v89
	ds_bpermute_b32 v98, v148, v90
	ds_bpermute_b32 v99, v148, v91
	v_pk_mul_f32 v[76:77], v[80:81], v[76:77]
	v_pk_mul_f32 v[78:79], v[82:83], v[78:79]
	v_pk_mul_f32 v[68:69], v[72:73], v[68:69]
	v_pk_mul_f32 v[70:71], v[74:75], v[70:71]
	v_pk_mul_f32 v[80:81], v[80:81], v[176:177] op_sel_hi:[1,0]
	v_pk_mul_f32 v[82:83], v[82:83], v[176:177] op_sel_hi:[1,0]
	v_pk_mul_f32 v[72:73], v[72:73], v[176:177] op_sel_hi:[1,0]
	v_pk_mul_f32 v[74:75], v[74:75], v[176:177] op_sel_hi:[1,0]
	v_exp_f32_e32 v80, v80
	v_exp_f32_e32 v81, v81
	v_exp_f32_e32 v82, v82
	v_exp_f32_e32 v83, v83
	v_exp_f32_e32 v72, v72
	v_exp_f32_e32 v73, v73
	v_exp_f32_e32 v74, v74
	v_exp_f32_e32 v75, v75
	v_pk_fma_f32 v[80:81], v[80:81], v[212:213], v[212:213] op_sel_hi:[1,0,0]
	v_pk_fma_f32 v[82:83], v[82:83], v[212:213], v[212:213] op_sel_hi:[1,0,0]
	v_pk_fma_f32 v[72:73], v[72:73], v[212:213], v[212:213] op_sel_hi:[1,0,0]
	v_pk_fma_f32 v[74:75], v[74:75], v[212:213], v[212:213] op_sel_hi:[1,0,0]
	v_rcp_f32_e32 v80, v80
	v_rcp_f32_e32 v81, v81
	v_rcp_f32_e32 v82, v82
	v_rcp_f32_e32 v83, v83
	v_rcp_f32_e32 v72, v72
	v_rcp_f32_e32 v73, v73
	v_rcp_f32_e32 v74, v74
	v_rcp_f32_e32 v75, v75
	v_pk_mul_f32 v[76:77], v[76:77], v[80:81]
	v_pk_mul_f32 v[78:79], v[78:79], v[82:83]
	v_pk_mul_f32 v[68:69], v[68:69], v[72:73]
	v_pk_mul_f32 v[70:71], v[70:71], v[74:75]
	v_cvt_pk_bf16_f32 v72, v76, v77
	v_cvt_pk_bf16_f32 v73, v78, v79
	v_cvt_pk_bf16_f32 v74, v68, v69
	v_cvt_pk_bf16_f32 v75, v70, v71
	s_waitcnt lgkmcnt(0)
	global_store_dwordx4 v[192:193], v[96:99], off
	v_lshl_add_u64 v[192:193], v[192:193], 0, s[28:29]
	ds_bpermute_b32 v80, v148, v72
	ds_bpermute_b32 v81, v148, v73
	ds_bpermute_b32 v82, v148, v74
	ds_bpermute_b32 v83, v148, v75
	v_pk_mul_f32 v[60:61], v[64:65], v[60:61]
	v_pk_mul_f32 v[62:63], v[66:67], v[62:63]
	v_pk_mul_f32 v[52:53], v[56:57], v[52:53]
	v_pk_mul_f32 v[54:55], v[58:59], v[54:55]
	v_pk_mul_f32 v[64:65], v[64:65], v[178:179] op_sel_hi:[1,0]
	v_pk_mul_f32 v[66:67], v[66:67], v[178:179] op_sel_hi:[1,0]
	v_pk_mul_f32 v[56:57], v[56:57], v[178:179] op_sel_hi:[1,0]
	v_pk_mul_f32 v[58:59], v[58:59], v[178:179] op_sel_hi:[1,0]
	v_exp_f32_e32 v64, v64
	v_exp_f32_e32 v65, v65
	v_exp_f32_e32 v66, v66
	v_exp_f32_e32 v67, v67
	v_exp_f32_e32 v56, v56
	v_exp_f32_e32 v57, v57
	v_exp_f32_e32 v58, v58
	v_exp_f32_e32 v59, v59
	v_pk_fma_f32 v[64:65], v[64:65], v[214:215], v[214:215] op_sel_hi:[1,0,0]
	v_pk_fma_f32 v[66:67], v[66:67], v[214:215], v[214:215] op_sel_hi:[1,0,0]
	v_pk_fma_f32 v[56:57], v[56:57], v[214:215], v[214:215] op_sel_hi:[1,0,0]
	v_pk_fma_f32 v[58:59], v[58:59], v[214:215], v[214:215] op_sel_hi:[1,0,0]
	v_rcp_f32_e32 v64, v64
	v_rcp_f32_e32 v65, v65
	v_rcp_f32_e32 v66, v66
	v_rcp_f32_e32 v67, v67
	v_rcp_f32_e32 v56, v56
	v_rcp_f32_e32 v57, v57
	v_rcp_f32_e32 v58, v58
	v_rcp_f32_e32 v59, v59
	v_pk_mul_f32 v[60:61], v[60:61], v[64:65]
	v_pk_mul_f32 v[62:63], v[62:63], v[66:67]
	v_pk_mul_f32 v[52:53], v[52:53], v[56:57]
	v_pk_mul_f32 v[54:55], v[54:55], v[58:59]
	v_cvt_pk_bf16_f32 v56, v60, v61
	v_cvt_pk_bf16_f32 v57, v62, v63
	v_cvt_pk_bf16_f32 v58, v52, v53
	v_cvt_pk_bf16_f32 v59, v54, v55
	s_waitcnt lgkmcnt(0)
	global_store_dwordx4 v[192:193], v[80:83], off
	s_mov_b32 s28, 0x6e000
	s_nop 0
	v_lshl_add_u64 v[192:193], v[192:193], 0, s[28:29]
	s_mov_b32 s28, 0x16000
	ds_bpermute_b32 v64, v148, v56
	ds_bpermute_b32 v65, v148, v57
	ds_bpermute_b32 v66, v148, v58
	ds_bpermute_b32 v67, v148, v59
	v_pk_mul_f32 v[44:45], v[48:49], v[44:45]
	v_pk_mul_f32 v[46:47], v[50:51], v[46:47]
	v_pk_mul_f32 v[36:37], v[40:41], v[36:37]
	v_pk_mul_f32 v[38:39], v[42:43], v[38:39]
	v_pk_mul_f32 v[48:49], v[48:49], v[180:181] op_sel_hi:[1,0]
	v_pk_mul_f32 v[50:51], v[50:51], v[180:181] op_sel_hi:[1,0]
	v_pk_mul_f32 v[40:41], v[40:41], v[180:181] op_sel_hi:[1,0]
	v_pk_mul_f32 v[42:43], v[42:43], v[180:181] op_sel_hi:[1,0]
	v_exp_f32_e32 v48, v48
	v_exp_f32_e32 v49, v49
	v_exp_f32_e32 v50, v50
	v_exp_f32_e32 v51, v51
	v_exp_f32_e32 v40, v40
	v_exp_f32_e32 v41, v41
	v_exp_f32_e32 v42, v42
	v_exp_f32_e32 v43, v43
	v_pk_fma_f32 v[48:49], v[48:49], v[216:217], v[216:217] op_sel_hi:[1,0,0]
	v_pk_fma_f32 v[50:51], v[50:51], v[216:217], v[216:217] op_sel_hi:[1,0,0]
	v_pk_fma_f32 v[40:41], v[40:41], v[216:217], v[216:217] op_sel_hi:[1,0,0]
	v_pk_fma_f32 v[42:43], v[42:43], v[216:217], v[216:217] op_sel_hi:[1,0,0]
	v_rcp_f32_e32 v48, v48
	v_rcp_f32_e32 v49, v49
	v_rcp_f32_e32 v50, v50
	v_rcp_f32_e32 v51, v51
	v_rcp_f32_e32 v40, v40
	v_rcp_f32_e32 v41, v41
	v_rcp_f32_e32 v42, v42
	v_rcp_f32_e32 v43, v43
	v_pk_mul_f32 v[44:45], v[44:45], v[48:49]
	v_pk_mul_f32 v[46:47], v[46:47], v[50:51]
	v_pk_mul_f32 v[36:37], v[36:37], v[40:41]
	v_pk_mul_f32 v[38:39], v[38:39], v[42:43]
	v_cvt_pk_bf16_f32 v40, v44, v45
	v_cvt_pk_bf16_f32 v41, v46, v47
	v_cvt_pk_bf16_f32 v42, v36, v37
	v_cvt_pk_bf16_f32 v43, v38, v39
	s_waitcnt lgkmcnt(0)
	global_store_dwordx4 v[192:193], v[64:67], off
	v_lshl_add_u64 v[192:193], v[192:193], 0, s[28:29]
	ds_bpermute_b32 v48, v148, v40
	ds_bpermute_b32 v49, v148, v41
	ds_bpermute_b32 v50, v148, v42
	ds_bpermute_b32 v51, v148, v43
	v_pk_mul_f32 v[28:29], v[32:33], v[28:29]
	v_pk_mul_f32 v[30:31], v[34:35], v[30:31]
	v_pk_mul_f32 v[20:21], v[24:25], v[20:21]
	v_pk_mul_f32 v[22:23], v[26:27], v[22:23]
	v_pk_mul_f32 v[32:33], v[32:33], v[182:183] op_sel_hi:[1,0]
	v_pk_mul_f32 v[34:35], v[34:35], v[182:183] op_sel_hi:[1,0]
	v_pk_mul_f32 v[24:25], v[24:25], v[182:183] op_sel_hi:[1,0]
	v_pk_mul_f32 v[26:27], v[26:27], v[182:183] op_sel_hi:[1,0]
	v_exp_f32_e32 v32, v32
	v_exp_f32_e32 v33, v33
	v_exp_f32_e32 v34, v34
	v_exp_f32_e32 v35, v35
	v_exp_f32_e32 v24, v24
	v_exp_f32_e32 v25, v25
	v_exp_f32_e32 v26, v26
	v_exp_f32_e32 v27, v27
	v_pk_fma_f32 v[32:33], v[32:33], v[218:219], v[218:219] op_sel_hi:[1,0,0]
	v_pk_fma_f32 v[34:35], v[34:35], v[218:219], v[218:219] op_sel_hi:[1,0,0]
	v_pk_fma_f32 v[24:25], v[24:25], v[218:219], v[218:219] op_sel_hi:[1,0,0]
	v_pk_fma_f32 v[26:27], v[26:27], v[218:219], v[218:219] op_sel_hi:[1,0,0]
	v_rcp_f32_e32 v32, v32
	v_rcp_f32_e32 v33, v33
	v_rcp_f32_e32 v34, v34
	v_rcp_f32_e32 v35, v35
	v_rcp_f32_e32 v24, v24
	v_rcp_f32_e32 v25, v25
	v_rcp_f32_e32 v26, v26
	v_rcp_f32_e32 v27, v27
	v_pk_mul_f32 v[28:29], v[28:29], v[32:33]
	v_pk_mul_f32 v[30:31], v[30:31], v[34:35]
	v_pk_mul_f32 v[20:21], v[20:21], v[24:25]
	v_pk_mul_f32 v[22:23], v[22:23], v[26:27]
	v_cvt_pk_bf16_f32 v24, v28, v29
	v_cvt_pk_bf16_f32 v25, v30, v31
	v_cvt_pk_bf16_f32 v26, v20, v21
	v_cvt_pk_bf16_f32 v27, v22, v23
	s_waitcnt lgkmcnt(0)
	global_store_dwordx4 v[192:193], v[48:51], off
	v_lshl_add_u64 v[192:193], v[192:193], 0, s[28:29]
	ds_bpermute_b32 v32, v148, v24
	ds_bpermute_b32 v33, v148, v25
	ds_bpermute_b32 v34, v148, v26
	ds_bpermute_b32 v35, v148, v27
	v_pk_mul_f32 v[12:13], v[16:17], v[12:13]
	v_pk_mul_f32 v[14:15], v[18:19], v[14:15]
	v_pk_mul_f32 v[4:5], v[8:9], v[4:5]
	v_pk_mul_f32 v[6:7], v[10:11], v[6:7]
	v_pk_mul_f32 v[16:17], v[16:17], v[184:185] op_sel_hi:[1,0]
	v_pk_mul_f32 v[18:19], v[18:19], v[184:185] op_sel_hi:[1,0]
	v_pk_mul_f32 v[8:9], v[8:9], v[184:185] op_sel_hi:[1,0]
	v_pk_mul_f32 v[10:11], v[10:11], v[184:185] op_sel_hi:[1,0]
	v_exp_f32_e32 v16, v16
	v_exp_f32_e32 v17, v17
	v_exp_f32_e32 v18, v18
	v_exp_f32_e32 v19, v19
	v_exp_f32_e32 v8, v8
	v_exp_f32_e32 v9, v9
	v_exp_f32_e32 v10, v10
	v_exp_f32_e32 v11, v11
	v_pk_fma_f32 v[16:17], v[16:17], v[220:221], v[220:221] op_sel_hi:[1,0,0]
	v_pk_fma_f32 v[18:19], v[18:19], v[220:221], v[220:221] op_sel_hi:[1,0,0]
	v_pk_fma_f32 v[8:9], v[8:9], v[220:221], v[220:221] op_sel_hi:[1,0,0]
	v_pk_fma_f32 v[10:11], v[10:11], v[220:221], v[220:221] op_sel_hi:[1,0,0]
	v_rcp_f32_e32 v16, v16
	v_rcp_f32_e32 v17, v17
	v_rcp_f32_e32 v18, v18
	v_rcp_f32_e32 v19, v19
	v_rcp_f32_e32 v8, v8
	v_rcp_f32_e32 v9, v9
	v_rcp_f32_e32 v10, v10
	v_rcp_f32_e32 v11, v11
	v_pk_mul_f32 v[12:13], v[12:13], v[16:17]
	v_pk_mul_f32 v[14:15], v[14:15], v[18:19]
	v_pk_mul_f32 v[4:5], v[4:5], v[8:9]
	v_pk_mul_f32 v[6:7], v[6:7], v[10:11]
	v_cvt_pk_bf16_f32 v8, v12, v13
	v_cvt_pk_bf16_f32 v9, v14, v15
	v_cvt_pk_bf16_f32 v10, v4, v5
	v_cvt_pk_bf16_f32 v11, v6, v7
	s_waitcnt lgkmcnt(0)
	global_store_dwordx4 v[192:193], v[32:35], off
	v_lshl_add_u64 v[192:193], v[192:193], 0, s[28:29]
	ds_bpermute_b32 v16, v148, v8
	ds_bpermute_b32 v17, v148, v9
	ds_bpermute_b32 v18, v148, v10
	ds_bpermute_b32 v19, v148, v11
	s_andn2_b64 vcc, exec, s[38:39]
	s_mov_b64 s[28:29], -1
	s_waitcnt lgkmcnt(0)
	global_store_dwordx4 v[192:193], v[16:19], off
	s_cbranch_vccnz .LBB0_308
	s_andn2_b64 vcc, exec, s[14:15]
	s_cbranch_vccnz .LBB0_307
	s_barrier
	s_branch .LBB0_307

.LBB0_752:
	s_add_u32 s20, s18, 0xfffc0080
	s_addc_u32 s21, s19, -1
	s_add_i32 s41, 0, 0x10000
	s_cmp_eq_u32 s40, 12
	s_cselect_b32 s23, s15, s21
	s_cselect_b32 s22, s17, s20
	v_add_u32_e32 v2, s41, v157
	s_cselect_b32 s21, s24, s27
	s_cselect_b32 s20, s25, s26
	s_add_i32 s55, 0, 0x14000
	ds_read_b128 v[144:147], v2
	ds_read_b128 v[148:151], v2 offset:1024
	ds_read_b128 v[152:155], v2 offset:2048
	ds_read_b128 v[160:163], v2 offset:3072
	v_add_u32_e32 v2, s55, v157
	ds_read_b128 v[164:167], v2
	ds_read_b128 v[168:171], v2 offset:1024
	ds_read_b128 v[172:175], v2 offset:2048
	ds_read_b128 v[176:179], v2 offset:3072
	v_lshl_add_u64 v[234:235], s[18:19], 0, v[140:141]
	s_add_i32 m0, s36, 0xc000
	ds_read_b128 v[180:183], v158
	ds_read_b128 v[184:187], v158 offset:1024
	ds_read_b128 v[188:191], v158 offset:2048
	ds_read_b128 v[192:195], v158 offset:3072
	ds_read_b128 v[206:209], v158 offset:4096
	ds_read_b128 v[210:213], v158 offset:5120
	ds_read_b128 v[214:217], v158 offset:6144
	ds_read_b128 v[218:221], v158 offset:7168
	global_load_lds_dwordx4 v[234:235], off
	v_lshl_add_u64 v[234:235], s[18:19], 0, v[142:143]
	s_add_i32 m0, s36, 0xe000
	s_nop 0
	global_load_lds_dwordx4 v[234:235], off
	s_waitcnt vmcnt(8)
	s_waitcnt lgkmcnt(0)
	s_barrier
	s_waitcnt lgkmcnt(0)
	v_mfma_f32_16x16x32_bf16 v[120:123], v[144:147], v[180:183], v[120:123]
	v_mfma_f32_16x16x32_bf16 v[116:119], v[152:155], v[180:183], v[116:119]
	v_mfma_f32_16x16x32_bf16 v[104:107], v[144:147], v[188:191], v[104:107]
	v_mfma_f32_16x16x32_bf16 v[100:103], v[152:155], v[188:191], v[100:103]
	v_mfma_f32_16x16x32_bf16 v[88:91], v[144:147], v[206:209], v[88:91]
	v_mfma_f32_16x16x32_bf16 v[84:87], v[152:155], v[206:209], v[84:87]
	v_mfma_f32_16x16x32_bf16 v[72:75], v[144:147], v[214:217], v[72:75]
	v_mfma_f32_16x16x32_bf16 v[68:71], v[152:155], v[214:217], v[68:71]
	v_mfma_f32_16x16x32_bf16 v[120:123], v[148:151], v[184:187], v[120:123]
	v_mfma_f32_16x16x32_bf16 v[116:119], v[160:163], v[184:187], v[116:119]
	v_mfma_f32_16x16x32_bf16 v[104:107], v[148:151], v[192:195], v[104:107]
	v_mfma_f32_16x16x32_bf16 v[100:103], v[160:163], v[192:195], v[100:103]
	v_mfma_f32_16x16x32_bf16 v[88:91], v[148:151], v[210:213], v[88:91]
	v_mfma_f32_16x16x32_bf16 v[84:87], v[160:163], v[210:213], v[84:87]
	v_mfma_f32_16x16x32_bf16 v[72:75], v[148:151], v[218:221], v[72:75]
	v_mfma_f32_16x16x32_bf16 v[68:71], v[160:163], v[218:221], v[68:71]
	v_mfma_f32_16x16x32_bf16 v[128:131], v[164:167], v[180:183], v[128:131]
	v_mfma_f32_16x16x32_bf16 v[124:127], v[172:175], v[180:183], v[124:127]
	v_mfma_f32_16x16x32_bf16 v[112:115], v[164:167], v[188:191], v[112:115]
	v_mfma_f32_16x16x32_bf16 v[108:111], v[172:175], v[188:191], v[108:111]
	v_mfma_f32_16x16x32_bf16 v[96:99], v[164:167], v[206:209], v[96:99]
	v_mfma_f32_16x16x32_bf16 v[92:95], v[172:175], v[206:209], v[92:95]
	v_mfma_f32_16x16x32_bf16 v[80:83], v[164:167], v[214:217], v[80:83]
	v_mfma_f32_16x16x32_bf16 v[76:79], v[172:175], v[214:217], v[76:79]
	v_mfma_f32_16x16x32_bf16 v[128:131], v[168:171], v[184:187], v[128:131]
	v_mfma_f32_16x16x32_bf16 v[124:127], v[176:179], v[184:187], v[124:127]
	v_mfma_f32_16x16x32_bf16 v[112:115], v[168:171], v[192:195], v[112:115]
	v_mfma_f32_16x16x32_bf16 v[108:111], v[176:179], v[192:195], v[108:111]
	v_mfma_f32_16x16x32_bf16 v[96:99], v[168:171], v[210:213], v[96:99]
	v_mfma_f32_16x16x32_bf16 v[92:95], v[176:179], v[210:213], v[92:95]
	v_mfma_f32_16x16x32_bf16 v[80:83], v[168:171], v[218:221], v[80:83]
	v_mfma_f32_16x16x32_bf16 v[76:79], v[176:179], v[218:221], v[76:79]
	s_barrier
	s_add_i32 s41, s41, s35
	v_lshl_add_u64 v[234:235], s[20:21], 0, v[134:135]
	s_mov_b32 m0, s41
	ds_read_b128 v[180:183], v158 offset:16384
	ds_read_b128 v[184:187], v158 offset:17408
	ds_read_b128 v[188:191], v158 offset:18432
	ds_read_b128 v[192:195], v158 offset:19456
	ds_read_b128 v[206:209], v158 offset:20480
	ds_read_b128 v[210:213], v158 offset:21504
	ds_read_b128 v[214:217], v158 offset:22528
	ds_read_b128 v[218:221], v158 offset:23552
	global_load_lds_dwordx4 v[234:235], off
	s_add_i32 m0, s41, 0x2000
	s_add_u32 s42, s20, 0x40000
	v_lshl_add_u64 v[236:237], s[20:21], 0, v[138:139]
	s_addc_u32 s43, s21, 0
	s_add_i32 s41, s55, s35
	global_load_lds_dwordx4 v[236:237], off
	v_lshl_add_u64 v[238:239], s[42:43], 0, v[134:135]
	s_mov_b32 m0, s41
	v_lshl_add_u64 v[240:241], s[22:23], 0, v[136:137]
	global_load_lds_dwordx4 v[238:239], off
	v_lshl_add_u64 v[238:239], s[42:43], 0, v[138:139]
	s_add_i32 m0, s41, 0x2000
	s_nop 0
	global_load_lds_dwordx4 v[238:239], off
	v_lshl_add_u64 v[238:239], s[22:23], 0, v[132:133]
	s_mov_b32 m0, s36
	s_nop 0
	global_load_lds_dwordx4 v[238:239], off
	s_mov_b32 m0, s37
	s_nop 0
	global_load_lds_dwordx4 v[240:241], off
	s_waitcnt vmcnt(8)
	s_waitcnt lgkmcnt(0)
	s_barrier
	s_waitcnt lgkmcnt(0)
	v_mfma_f32_16x16x32_bf16 v[56:59], v[144:147], v[180:183], v[56:59]
	v_mfma_f32_16x16x32_bf16 v[52:55], v[152:155], v[180:183], v[52:55]
	v_mfma_f32_16x16x32_bf16 v[40:43], v[144:147], v[188:191], v[40:43]
	v_mfma_f32_16x16x32_bf16 v[36:39], v[152:155], v[188:191], v[36:39]
	v_mfma_f32_16x16x32_bf16 v[24:27], v[144:147], v[206:209], v[24:27]
	v_mfma_f32_16x16x32_bf16 v[20:23], v[152:155], v[206:209], v[20:23]
	v_mfma_f32_16x16x32_bf16 v[8:11], v[144:147], v[214:217], v[8:11]
	v_mfma_f32_16x16x32_bf16 v[4:7], v[152:155], v[214:217], v[4:7]
	v_mfma_f32_16x16x32_bf16 v[56:59], v[148:151], v[184:187], v[56:59]
	v_mfma_f32_16x16x32_bf16 v[52:55], v[160:163], v[184:187], v[52:55]
	v_mfma_f32_16x16x32_bf16 v[40:43], v[148:151], v[192:195], v[40:43]
	v_mfma_f32_16x16x32_bf16 v[36:39], v[160:163], v[192:195], v[36:39]
	v_mfma_f32_16x16x32_bf16 v[24:27], v[148:151], v[210:213], v[24:27]
	v_mfma_f32_16x16x32_bf16 v[20:23], v[160:163], v[210:213], v[20:23]
	v_mfma_f32_16x16x32_bf16 v[8:11], v[148:151], v[218:221], v[8:11]
	v_mfma_f32_16x16x32_bf16 v[4:7], v[160:163], v[218:221], v[4:7]
	v_mfma_f32_16x16x32_bf16 v[64:67], v[164:167], v[180:183], v[64:67]
	v_mfma_f32_16x16x32_bf16 v[60:63], v[172:175], v[180:183], v[60:63]
	v_mfma_f32_16x16x32_bf16 v[48:51], v[164:167], v[188:191], v[48:51]
	v_mfma_f32_16x16x32_bf16 v[44:47], v[172:175], v[188:191], v[44:47]
	v_mfma_f32_16x16x32_bf16 v[32:35], v[164:167], v[206:209], v[32:35]
	v_mfma_f32_16x16x32_bf16 v[28:31], v[172:175], v[206:209], v[28:31]
	v_mfma_f32_16x16x32_bf16 v[16:19], v[164:167], v[214:217], v[16:19]
	v_mfma_f32_16x16x32_bf16 v[12:15], v[172:175], v[214:217], v[12:15]
	v_mfma_f32_16x16x32_bf16 v[64:67], v[168:171], v[184:187], v[64:67]
	v_mfma_f32_16x16x32_bf16 v[60:63], v[176:179], v[184:187], v[60:63]
	v_mfma_f32_16x16x32_bf16 v[48:51], v[168:171], v[192:195], v[48:51]
	v_mfma_f32_16x16x32_bf16 v[44:47], v[176:179], v[192:195], v[44:47]
	v_mfma_f32_16x16x32_bf16 v[32:35], v[168:171], v[210:213], v[32:35]
	v_mfma_f32_16x16x32_bf16 v[28:31], v[176:179], v[210:213], v[28:31]
	v_mfma_f32_16x16x32_bf16 v[16:19], v[168:171], v[218:221], v[16:19]
	v_mfma_f32_16x16x32_bf16 v[12:15], v[176:179], v[218:221], v[12:15]
	s_barrier
	s_add_i32 s41, 0, 0x18000
	v_add_u32_e32 v2, s41, v157
	s_add_i32 s42, 0, 0x1c000
	ds_read_b128 v[144:147], v2
	ds_read_b128 v[148:151], v2 offset:1024
	ds_read_b128 v[152:155], v2 offset:2048
	ds_read_b128 v[160:163], v2 offset:3072
	v_add_u32_e32 v2, s42, v157
	ds_read_b128 v[164:167], v2
	ds_read_b128 v[168:171], v2 offset:1024
	ds_read_b128 v[172:175], v2 offset:2048
	ds_read_b128 v[176:179], v2 offset:3072
	s_add_u32 s22, s22, 0x40000
	s_addc_u32 s23, s23, 0
	s_mov_b32 m0, s64
	v_lshl_add_u64 v[242:243], s[22:23], 0, v[132:133]
	ds_read_b128 v[180:183], v158 offset:32768
	ds_read_b128 v[184:187], v158 offset:33792
	ds_read_b128 v[188:191], v158 offset:34816
	ds_read_b128 v[192:195], v158 offset:35840
	ds_read_b128 v[206:209], v158 offset:36864
	ds_read_b128 v[210:213], v158 offset:37888
	ds_read_b128 v[214:217], v158 offset:38912
	ds_read_b128 v[218:221], v158 offset:39936
	global_load_lds_dwordx4 v[242:243], off
	v_lshl_add_u64 v[242:243], s[22:23], 0, v[136:137]
	s_mov_b32 m0, s65
	s_nop 0
	global_load_lds_dwordx4 v[242:243], off
	s_waitcnt vmcnt(8)
	s_waitcnt lgkmcnt(0)
	s_barrier
	s_waitcnt lgkmcnt(0)
	v_mfma_f32_16x16x32_bf16 v[120:123], v[144:147], v[180:183], v[120:123]
	v_mfma_f32_16x16x32_bf16 v[116:119], v[152:155], v[180:183], v[116:119]
	v_mfma_f32_16x16x32_bf16 v[104:107], v[144:147], v[188:191], v[104:107]
	v_mfma_f32_16x16x32_bf16 v[100:103], v[152:155], v[188:191], v[100:103]
	v_mfma_f32_16x16x32_bf16 v[88:91], v[144:147], v[206:209], v[88:91]
	v_mfma_f32_16x16x32_bf16 v[84:87], v[152:155], v[206:209], v[84:87]
	v_mfma_f32_16x16x32_bf16 v[72:75], v[144:147], v[214:217], v[72:75]
	v_mfma_f32_16x16x32_bf16 v[68:71], v[152:155], v[214:217], v[68:71]
	v_mfma_f32_16x16x32_bf16 v[120:123], v[148:151], v[184:187], v[120:123]
	v_mfma_f32_16x16x32_bf16 v[116:119], v[160:163], v[184:187], v[116:119]
	v_mfma_f32_16x16x32_bf16 v[104:107], v[148:151], v[192:195], v[104:107]
	v_mfma_f32_16x16x32_bf16 v[100:103], v[160:163], v[192:195], v[100:103]
	v_mfma_f32_16x16x32_bf16 v[88:91], v[148:151], v[210:213], v[88:91]
	v_mfma_f32_16x16x32_bf16 v[84:87], v[160:163], v[210:213], v[84:87]
	v_mfma_f32_16x16x32_bf16 v[72:75], v[148:151], v[218:221], v[72:75]
	v_mfma_f32_16x16x32_bf16 v[68:71], v[160:163], v[218:221], v[68:71]
	v_mfma_f32_16x16x32_bf16 v[128:131], v[164:167], v[180:183], v[128:131]
	v_mfma_f32_16x16x32_bf16 v[124:127], v[172:175], v[180:183], v[124:127]
	v_mfma_f32_16x16x32_bf16 v[112:115], v[164:167], v[188:191], v[112:115]
	v_mfma_f32_16x16x32_bf16 v[108:111], v[172:175], v[188:191], v[108:111]
	v_mfma_f32_16x16x32_bf16 v[96:99], v[164:167], v[206:209], v[96:99]
	v_mfma_f32_16x16x32_bf16 v[92:95], v[172:175], v[206:209], v[92:95]
	v_mfma_f32_16x16x32_bf16 v[80:83], v[164:167], v[214:217], v[80:83]
	v_mfma_f32_16x16x32_bf16 v[76:79], v[172:175], v[214:217], v[76:79]
	v_mfma_f32_16x16x32_bf16 v[128:131], v[168:171], v[184:187], v[128:131]
	v_mfma_f32_16x16x32_bf16 v[124:127], v[176:179], v[184:187], v[124:127]
	v_mfma_f32_16x16x32_bf16 v[112:115], v[168:171], v[192:195], v[112:115]
	v_mfma_f32_16x16x32_bf16 v[108:111], v[176:179], v[192:195], v[108:111]
	v_mfma_f32_16x16x32_bf16 v[96:99], v[168:171], v[210:213], v[96:99]
	v_mfma_f32_16x16x32_bf16 v[92:95], v[176:179], v[210:213], v[92:95]
	v_mfma_f32_16x16x32_bf16 v[80:83], v[168:171], v[218:221], v[80:83]
	v_mfma_f32_16x16x32_bf16 v[76:79], v[176:179], v[218:221], v[76:79]
	s_barrier
	s_add_i32 s22, s41, s35
	v_lshl_add_u64 v[234:235], v[234:235], 0, s[96:97]
	s_mov_b32 m0, s22
	ds_read_b128 v[180:183], v158 offset:49152
	ds_read_b128 v[184:187], v158 offset:50176
	ds_read_b128 v[188:191], v158 offset:51200
	ds_read_b128 v[192:195], v158 offset:52224
	ds_read_b128 v[206:209], v158 offset:53248
	ds_read_b128 v[210:213], v158 offset:54272
	ds_read_b128 v[214:217], v158 offset:55296
	ds_read_b128 v[218:221], v158 offset:56320
	global_load_lds_dwordx4 v[234:235], off
	s_add_i32 m0, s22, 0x2000
	s_add_u32 s20, s20, 0x40080
	v_lshl_add_u64 v[234:235], v[236:237], 0, s[96:97]
	s_addc_u32 s21, s21, 0
	s_add_i32 s22, s42, s35
	global_load_lds_dwordx4 v[234:235], off
	v_lshl_add_u64 v[234:235], s[20:21], 0, v[134:135]
	s_mov_b32 m0, s22
	s_nop 0
	global_load_lds_dwordx4 v[234:235], off
	v_lshl_add_u64 v[234:235], s[20:21], 0, v[138:139]
	s_add_i32 m0, s22, 0x2000
	s_nop 0
	global_load_lds_dwordx4 v[234:235], off
	v_lshl_add_u64 v[234:235], v[238:239], 0, s[96:97]
	s_mov_b32 m0, s67
	s_nop 0
	global_load_lds_dwordx4 v[234:235], off
	v_lshl_add_u64 v[234:235], v[240:241], 0, s[96:97]
	s_mov_b32 m0, s68
	s_nop 0
	global_load_lds_dwordx4 v[234:235], off
	s_waitcnt vmcnt(8)
	s_waitcnt lgkmcnt(0)
	s_barrier
	s_waitcnt lgkmcnt(0)
	v_mfma_f32_16x16x32_bf16 v[56:59], v[144:147], v[180:183], v[56:59]
	v_mfma_f32_16x16x32_bf16 v[52:55], v[152:155], v[180:183], v[52:55]
	v_mfma_f32_16x16x32_bf16 v[40:43], v[144:147], v[188:191], v[40:43]
	v_mfma_f32_16x16x32_bf16 v[36:39], v[152:155], v[188:191], v[36:39]
	v_mfma_f32_16x16x32_bf16 v[24:27], v[144:147], v[206:209], v[24:27]
	v_mfma_f32_16x16x32_bf16 v[20:23], v[152:155], v[206:209], v[20:23]
	v_mfma_f32_16x16x32_bf16 v[8:11], v[144:147], v[214:217], v[8:11]
	v_mfma_f32_16x16x32_bf16 v[4:7], v[152:155], v[214:217], v[4:7]
	v_mfma_f32_16x16x32_bf16 v[56:59], v[148:151], v[184:187], v[56:59]
	v_mfma_f32_16x16x32_bf16 v[52:55], v[160:163], v[184:187], v[52:55]
	v_mfma_f32_16x16x32_bf16 v[40:43], v[148:151], v[192:195], v[40:43]
	v_mfma_f32_16x16x32_bf16 v[36:39], v[160:163], v[192:195], v[36:39]
	v_mfma_f32_16x16x32_bf16 v[24:27], v[148:151], v[210:213], v[24:27]
	v_mfma_f32_16x16x32_bf16 v[20:23], v[160:163], v[210:213], v[20:23]
	v_mfma_f32_16x16x32_bf16 v[8:11], v[148:151], v[218:221], v[8:11]
	v_mfma_f32_16x16x32_bf16 v[4:7], v[160:163], v[218:221], v[4:7]
	v_mfma_f32_16x16x32_bf16 v[64:67], v[164:167], v[180:183], v[64:67]
	v_mfma_f32_16x16x32_bf16 v[60:63], v[172:175], v[180:183], v[60:63]
	v_mfma_f32_16x16x32_bf16 v[48:51], v[164:167], v[188:191], v[48:51]
	v_mfma_f32_16x16x32_bf16 v[44:47], v[172:175], v[188:191], v[44:47]
	v_mfma_f32_16x16x32_bf16 v[32:35], v[164:167], v[206:209], v[32:35]
	v_mfma_f32_16x16x32_bf16 v[28:31], v[172:175], v[206:209], v[28:31]
	v_mfma_f32_16x16x32_bf16 v[16:19], v[164:167], v[214:217], v[16:19]
	v_mfma_f32_16x16x32_bf16 v[12:15], v[172:175], v[214:217], v[12:15]
	v_mfma_f32_16x16x32_bf16 v[64:67], v[168:171], v[184:187], v[64:67]
	v_mfma_f32_16x16x32_bf16 v[60:63], v[176:179], v[184:187], v[60:63]
	v_mfma_f32_16x16x32_bf16 v[48:51], v[168:171], v[192:195], v[48:51]
	v_mfma_f32_16x16x32_bf16 v[44:47], v[176:179], v[192:195], v[44:47]
	v_mfma_f32_16x16x32_bf16 v[32:35], v[168:171], v[210:213], v[32:35]
	v_mfma_f32_16x16x32_bf16 v[28:31], v[176:179], v[210:213], v[28:31]
	v_mfma_f32_16x16x32_bf16 v[16:19], v[168:171], v[218:221], v[16:19]
	v_mfma_f32_16x16x32_bf16 v[12:15], v[176:179], v[218:221], v[12:15]
	s_barrier
	s_add_i32 s40, s40, 2
	s_add_u32 s18, s18, 0x100
	s_addc_u32 s19, s19, 0
	s_add_u32 s26, s26, 0x100
	s_addc_u32 s27, s27, 0
	s_cmp_gt_u32 s40, 13
	s_cbranch_scc0 .LBB0_752
	s_and_b64 vcc, exec, s[46:47]
	s_cbranch_vccz .LBB0_755
	v_lshl_add_u32 v2, v156, 4, v1
	v_add_u32_e32 v2, s69, v2
	v_lshlrev_b32_e32 v164, 6, v2
	v_add_u32_e32 v164, 0x20400, v164
	ds_read_b128 v[148:151], v164
	ds_read_b128 v[152:155], v164 offset:32
	ds_read_b128 v[160:163], v164 offset:16
	ds_read_b128 v[164:167], v164 offset:48
	s_mov_b32 s15, 0x800000
	v_lshl_add_u32 v2, v2, 2, v225
	s_waitcnt lgkmcnt(0)
	v_mov_b32_e32 v168, v148
	v_mov_b32_e32 v169, v152
	v_mov_b32_e32 v152, v149
	v_mov_b32_e32 v148, v150
	v_mov_b32_e32 v149, v154
	v_mov_b32_e32 v154, v151
	v_mov_b32_e32 v150, v160
	v_mov_b32_e32 v151, v164
	v_mov_b32_e32 v164, v161
	v_mov_b32_e32 v160, v162
	v_mov_b32_e32 v161, v166
	v_mov_b32_e32 v166, v163
	v_pk_add_f32 v[152:153], v[168:169], v[152:153]
	v_pk_add_f32 v[148:149], v[148:149], v[154:155]
	v_pk_add_f32 v[150:151], v[150:151], v[164:165]
	v_pk_add_f32 v[154:155], v[160:161], v[166:167]
	v_pk_add_f32 v[148:149], v[152:153], v[148:149]
	v_pk_add_f32 v[150:151], v[150:151], v[154:155]
	s_nop 0
	v_pk_add_f32 v[148:149], v[148:149], v[150:151]
	s_nop 0
	v_add_f32_e32 v147, v148, v149
	v_fmamk_f32 v147, v147, 0x3a800000, v223
	v_mul_f32_e32 v148, 0x4b800000, v147
	v_cmp_gt_f32_e32 vcc, s15, v147
	s_nop 1
	v_cndmask_b32_e32 v147, v147, v148, vcc
	v_rsq_f32_e32 v147, v147
	s_nop 0
	v_mul_f32_e32 v148, 0x45800000, v147
	v_cndmask_b32_e32 v147, v147, v148, vcc
	ds_write_b32 v2, v147
	s_waitcnt lgkmcnt(0)
	s_barrier

.LBB0_757:
	s_nop 0
	s_nop 0
	s_nop 0
	s_cmp_gt_i32 s14, 1
	s_mov_b64 s[16:17], -1
	s_cbranch_scc0 .LBB0_774
	s_cmp_eq_u32 s14, 2
	s_mov_b64 s[16:17], 0
	s_cbranch_scc1 .LBB0_772
	s_cmp_gt_u32 s14, 6
	s_mov_b64 s[26:27], -1
	s_cbranch_scc0 .LBB0_770
	s_cmp_gt_u32 s14, 12
	s_cbranch_scc0 .LBB0_767
	s_cmp_gt_u32 s14, 16
	s_cbranch_scc0 .LBB0_764
	s_cmp_gt_u32 s14, 20
	s_mov_b64 s[26:27], 0
	s_cbranch_scc1 .LBB0_1115
	s_lshl_b32 s15, s14, 8
	s_add_i32 s20, s15, 0xffffef00
	s_mov_b64 s[24:25], 0
	s_mov_b64 s[18:19], -1
	s_mov_b64 s[62:63], 0x400
	s_mov_b64 s[22:23], 0xd120000
